# v12 + attention: QK^T fragment reads issued 14 ahead (counted lgkmcnt), softmax row-max via permlane16/32 swaps instead of ds_bpermute
# baseline (speedup 1.0000x reference)
; __device__ __forceinline__ unsigned cvt_pk_bf16(float lo, float hi) { unsigned r; asm volatile("v_cvt_pk_bf16_f32 %0, %1, %2" : "=v"(r) : "v"(lo), "v"(hi)); return r; }
; #define PG8_WAIT_V(n) asm volatile("s_waitcnt vmcnt(" #n ")" ::: "memory")
; #define PG8_BAR __builtin_amdgcn_s_barrier()
; template <class Epi, class Sched>
; __device__ __forceinline__ void gemm_phase(LAS unsigned char* lds, const Gemm g, const Sched& S, const Epi& E) {
;     ...
;     PG8_WAIT_V(0);
;     PG8_BAR;
;     const long total = (long)(K / 8) * Ndst;
; #pragma unroll 4
;     for (long it = gtid; it < total; it += gsz) {
;         const int n = (int)(it % Ndst), k8 = (int)(it / Ndst);
;         int sc = n;
;         if (MODE == 1) { if (n < 3584) sc = n; else sc = n + 16; }
;         u32x4 w = {0u, 0u, 0u, 0u};
;         if (sc >= 0) {
;             const float* s = src + (size_t)(k8 * 8) * Nsrc + sc;
;             float v0 = s[0], v1 = s[(size_t)Nsrc], v2 = s[(size_t)2 * Nsrc], v3 = s[(size_t)3 * Nsrc], v4 = s[(size_t)4 * Nsrc], v5 = s[(size_t)5 * Nsrc], v6 = s[(size_t)6 * Nsrc], v7 = s[(size_t)7 * Nsrc];
;             if (gain) { const f32x4 g0 = *(const f32x4*)(gain + k8 * 8), g1 = *(const f32x4*)(gain + k8 * 8 + 4); v0 *= g0[0]; v1 *= g0[1]; v2 *= g0[2]; v3 *= g0[3]; v4 *= g1[0]; v5 *= g1[1]; v6 *= g1[2]; v7 *= g1[3]; }
;             w.x = cvt_pk_bf16(v0 * wscale, v1 * wscale); w.y = cvt_pk_bf16(v2 * wscale, v3 * wscale); w.z = cvt_pk_bf16(v4 * wscale, v5 * wscale); w.w = cvt_pk_bf16(v6 * wscale, v7 * wscale);
;         }
;         *(u32x4*)(dst + (size_t)n * K + k8 * 8) = w;
.LBB0_238:
	s_waitcnt vmcnt(0)
	v_readlane_b32 s94, v250, 54
	v_readlane_b32 s92, v250, 52
	v_readlane_b32 s95, v250, 55
	v_readlane_b32 s93, v250, 53
	s_barrier
	s_cmpk_lg_i32 s94, 0x100
	s_cbranch_scc1 .Ldw_done
	s_cmpk_lt_u32 s2, 0xc0
	s_cbranch_scc1 .Ldw_done
	v_writelane_b32 v251, s0, 0
	v_writelane_b32 v251, s10, 1
	v_writelane_b32 v251, s11, 2
	v_writelane_b32 v251, s12, 3
	v_writelane_b32 v251, s13, 4
	v_writelane_b32 v251, s14, 5
	v_writelane_b32 v251, s15, 6
	v_writelane_b32 v251, s16, 7
	v_writelane_b32 v251, s17, 8
	v_writelane_b32 v251, s18, 9
	v_writelane_b32 v251, s19, 10
	v_writelane_b32 v251, s20, 11
	v_writelane_b32 v251, s21, 12
	v_writelane_b32 v251, s22, 13
	v_writelane_b32 v251, s23, 14
	v_writelane_b32 v251, s24, 15
	v_writelane_b32 v251, s25, 16
	v_writelane_b32 v251, s26, 17
	v_writelane_b32 v251, s27, 18
	v_writelane_b32 v251, s48, 19
	v_writelane_b32 v251, s49, 20
	v_writelane_b32 v251, s50, 21
	v_writelane_b32 v251, s51, 22
	v_writelane_b32 v251, s52, 23
	v_writelane_b32 v251, s53, 24
	v_writelane_b32 v251, s54, 25
	v_writelane_b32 v251, s55, 26
	v_writelane_b32 v251, s56, 27
	v_writelane_b32 v251, s57, 28
	v_writelane_b32 v251, s58, 29
	v_writelane_b32 v251, s59, 30
	v_writelane_b32 v251, s60, 31
	v_writelane_b32 v251, s61, 32
	v_writelane_b32 v251, s62, 33
	v_writelane_b32 v251, s63, 34
	v_lshrrev_b32_e32 v0, 6, v136
	s_sub_u32 s10, s2, 0xc0
	s_nop 0
	v_readfirstlane_b32 s0, v0
	v_and_b32_e32 v0, 63, v136
	s_lshl_b32 s10, s10, 3
	v_lshlrev_b32_e32 v2, 2, v0
	s_add_u32 s10, s10, s0
	s_mov_b32 s27, 0

; __device__ __forceinline__ unsigned cvt_pk_bf16(float lo, float hi) { unsigned r; asm volatile("v_cvt_pk_bf16_f32 %0, %1, %2" : "=v"(r) : "v"(lo), "v"(hi)); return r; }
;     ...
;         int sc = n;
;         if (MODE == 1) { if (n < 3584) sc = n; else sc = n + 16; }
;         u32x4 w = {0u, 0u, 0u, 0u};
;         if (sc >= 0) {
;             const float* s = src + (size_t)(k8 * 8) * Nsrc + sc;
;             float v0 = s[0], v1 = s[(size_t)Nsrc], v2 = s[(size_t)2 * Nsrc], v3 = s[(size_t)3 * Nsrc], v4 = s[(size_t)4 * Nsrc], v5 = s[(size_t)5 * Nsrc], v6 = s[(size_t)6 * Nsrc], v7 = s[(size_t)7 * Nsrc];
;             if (gain) { const f32x4 g0 = *(const f32x4*)(gain + k8 * 8), g1 = *(const f32x4*)(gain + k8 * 8 + 4); v0 *= g0[0]; v1 *= g0[1]; v2 *= g0[2]; v3 *= g0[3]; v4 *= g1[0]; v5 *= g1[1]; v6 *= g1[2]; v7 *= g1[3]; }
;             w.x = cvt_pk_bf16(v0 * wscale, v1 * wscale); w.y = cvt_pk_bf16(v2 * wscale, v3 * wscale); w.z = cvt_pk_bf16(v4 * wscale, v5 * wscale); w.w = cvt_pk_bf16(v6 * wscale, v7 * wscale);
.Ldw_go:
	s_lshl_b32 s21, s19, 5
	s_mul_i32 s24, s21, s14
	s_lshl_b32 s25, s18, 8
	s_add_u32 s24, s24, s25
	s_add_u32 s24, s24, s27
	s_add_u32 s12, s12, s24
	s_addc_u32 s13, s13, 0
	s_lshl_b32 s25, s18, 6
	v_add_u32_e32 v1, s25, v0
	v_mul_lo_u32 v4, v1, s15
	s_lshl_b32 s25, s19, 6
	s_add_u32 s16, s44, s20
	s_addc_u32 s17, s45, 0
	v_add_u32_e32 v4, s25, v4
	global_load_dword v8, v2, s[12:13] nt
	s_add_u32 s12, s12, s14
	s_addc_u32 s13, s13, 0
	global_load_dword v9, v2, s[12:13] nt
	s_add_u32 s12, s12, s14
	s_addc_u32 s13, s13, 0
	global_load_dword v10, v2, s[12:13] nt
	s_add_u32 s12, s12, s14
	s_addc_u32 s13, s13, 0
	global_load_dword v11, v2, s[12:13] nt
	s_add_u32 s12, s12, s14
	s_addc_u32 s13, s13, 0
	global_load_dword v12, v2, s[12:13] nt
	s_add_u32 s12, s12, s14
	s_addc_u32 s13, s13, 0
	global_load_dword v13, v2, s[12:13] nt
	s_add_u32 s12, s12, s14
	s_addc_u32 s13, s13, 0
	global_load_dword v14, v2, s[12:13] nt
	s_add_u32 s12, s12, s14
	s_addc_u32 s13, s13, 0
	global_load_dword v15, v2, s[12:13] nt
	s_add_u32 s12, s12, s14
	s_addc_u32 s13, s13, 0
	global_load_dword v16, v2, s[12:13] nt
	s_add_u32 s12, s12, s14
	s_addc_u32 s13, s13, 0
	global_load_dword v17, v2, s[12:13] nt
	s_add_u32 s12, s12, s14
	s_addc_u32 s13, s13, 0
	global_load_dword v18, v2, s[12:13] nt
	s_add_u32 s12, s12, s14
	s_addc_u32 s13, s13, 0
	global_load_dword v19, v2, s[12:13] nt
	s_add_u32 s12, s12, s14
	s_addc_u32 s13, s13, 0
	global_load_dword v20, v2, s[12:13] nt
	s_add_u32 s12, s12, s14
	s_addc_u32 s13, s13, 0
	global_load_dword v21, v2, s[12:13] nt
	s_add_u32 s12, s12, s14
	s_addc_u32 s13, s13, 0
	global_load_dword v22, v2, s[12:13] nt
	s_add_u32 s12, s12, s14
	s_addc_u32 s13, s13, 0
	global_load_dword v23, v2, s[12:13] nt
	s_add_u32 s12, s12, s14
	s_addc_u32 s13, s13, 0
	global_load_dword v24, v2, s[12:13] nt
	s_add_u32 s12, s12, s14
	s_addc_u32 s13, s13, 0
	global_load_dword v25, v2, s[12:13] nt
	s_add_u32 s12, s12, s14
	s_addc_u32 s13, s13, 0
	global_load_dword v26, v2, s[12:13] nt
	s_add_u32 s12, s12, s14
	s_addc_u32 s13, s13, 0
	global_load_dword v27, v2, s[12:13] nt
	s_add_u32 s12, s12, s14
	s_addc_u32 s13, s13, 0
	global_load_dword v28, v2, s[12:13] nt
	s_add_u32 s12, s12, s14
	s_addc_u32 s13, s13, 0
	global_load_dword v29, v2, s[12:13] nt
	s_add_u32 s12, s12, s14
	s_addc_u32 s13, s13, 0
	global_load_dword v30, v2, s[12:13] nt
	s_add_u32 s12, s12, s14
	s_addc_u32 s13, s13, 0
	global_load_dword v31, v2, s[12:13] nt
	s_add_u32 s12, s12, s14
	s_addc_u32 s13, s13, 0
	global_load_dword v32, v2, s[12:13] nt
	s_add_u32 s12, s12, s14
	s_addc_u32 s13, s13, 0
	global_load_dword v33, v2, s[12:13] nt
	s_add_u32 s12, s12, s14
	s_addc_u32 s13, s13, 0
	global_load_dword v34, v2, s[12:13] nt
	s_add_u32 s12, s12, s14
	s_addc_u32 s13, s13, 0
	global_load_dword v35, v2, s[12:13] nt
	s_add_u32 s12, s12, s14
	s_addc_u32 s13, s13, 0
	global_load_dword v36, v2, s[12:13] nt
	s_add_u32 s12, s12, s14
	s_addc_u32 s13, s13, 0
	global_load_dword v37, v2, s[12:13] nt
	s_add_u32 s12, s12, s14
	s_addc_u32 s13, s13, 0
	global_load_dword v38, v2, s[12:13] nt
	s_add_u32 s12, s12, s14
	s_addc_u32 s13, s13, 0
	global_load_dword v39, v2, s[12:13] nt
	s_cmp_eq_u32 s26, 0
	s_cbranch_scc1 .Ldw_nogain
	s_lshl_b32 s25, s21, 2
	s_add_u32 s22, s22, s25
	s_addc_u32 s23, s23, 0
	s_load_dwordx16 s[48:63], s[22:23], 0x0
	s_waitcnt vmcnt(16) lgkmcnt(0)
	v_mul_f32_e32 v8, s48, v8
	v_mul_f32_e32 v9, s49, v9
	v_mul_f32_e32 v10, s50, v10
	v_mul_f32_e32 v11, s51, v11
	v_mul_f32_e32 v12, s52, v12
	v_mul_f32_e32 v13, s53, v13
	v_mul_f32_e32 v14, s54, v14
	v_mul_f32_e32 v15, s55, v15
	v_mul_f32_e32 v16, s56, v16
	v_mul_f32_e32 v17, s57, v17
	v_mul_f32_e32 v18, s58, v18
	v_mul_f32_e32 v19, s59, v19
	v_mul_f32_e32 v20, s60, v20
	v_mul_f32_e32 v21, s61, v21
	v_mul_f32_e32 v22, s62, v22
	v_mul_f32_e32 v23, s63, v23
	s_nop 0
	s_load_dwordx16 s[48:63], s[22:23], 0x40
	s_waitcnt vmcnt(0) lgkmcnt(0)
	v_mul_f32_e32 v24, s48, v24
	v_mul_f32_e32 v25, s49, v25
	v_mul_f32_e32 v26, s50, v26
	v_mul_f32_e32 v27, s51, v27
	v_mul_f32_e32 v28, s52, v28
	v_mul_f32_e32 v29, s53, v29
	v_mul_f32_e32 v30, s54, v30
	v_mul_f32_e32 v31, s55, v31
	v_mul_f32_e32 v32, s56, v32
	v_mul_f32_e32 v33, s57, v33
	v_mul_f32_e32 v34, s58, v34
	v_mul_f32_e32 v35, s59, v35
	v_mul_f32_e32 v36, s60, v36
	v_mul_f32_e32 v37, s61, v37
	v_mul_f32_e32 v38, s62, v38
	v_mul_f32_e32 v39, s63, v39

;     ...
; }
.Ldw_end:
	v_readlane_b32 s0, v251, 0
	v_readlane_b32 s10, v251, 1
	v_readlane_b32 s11, v251, 2
	v_readlane_b32 s12, v251, 3
	v_readlane_b32 s13, v251, 4
	v_readlane_b32 s14, v251, 5
	v_readlane_b32 s15, v251, 6
	v_readlane_b32 s16, v251, 7
	v_readlane_b32 s17, v251, 8
	v_readlane_b32 s18, v251, 9
	v_readlane_b32 s19, v251, 10
	v_readlane_b32 s20, v251, 11
	v_readlane_b32 s21, v251, 12
	v_readlane_b32 s22, v251, 13
	v_readlane_b32 s23, v251, 14
	v_readlane_b32 s24, v251, 15
	v_readlane_b32 s25, v251, 16
	v_readlane_b32 s26, v251, 17
	v_readlane_b32 s27, v251, 18
	v_readlane_b32 s48, v251, 19
	v_readlane_b32 s49, v251, 20
	v_readlane_b32 s50, v251, 21
	v_readlane_b32 s51, v251, 22
	v_readlane_b32 s52, v251, 23
	v_readlane_b32 s53, v251, 24
	v_readlane_b32 s54, v251, 25
	v_readlane_b32 s55, v251, 26
	v_readlane_b32 s56, v251, 27
	v_readlane_b32 s57, v251, 28
	v_readlane_b32 s58, v251, 29
	v_readlane_b32 s59, v251, 30
	v_readlane_b32 s60, v251, 31
	v_readlane_b32 s61, v251, 32
	v_readlane_b32 s62, v251, 33
	v_readlane_b32 s63, v251, 34
	s_nop 0

; #define MFMA16(a, b, c) __builtin_amdgcn_mfma_f32_16x16x32_bf16((a), (b), (c), 0, 0, 0)
; __device__ __forceinline__ void attn_item(const Params& p, LAS unsigned char* L, int item, bf16_t* Yd, int ldd) {
;     ...
;         for (int kt = 0; kt < 12; ++kt)
; #pragma unroll
;             for (int jj = 0; jj < 4; ++jj) sacc[kt][jj] = fmaf(-slope, fabsf(dbase - (float)(kt * 16 + jj)), sacc[kt][jj]);
;         if (!smp && c < 2) {
; #pragma unroll
;             for (int kt = 0; kt < 8; ++kt)
; #pragma unroll
;                 for (int jj = 0; jj < 4; ++jj) { const int j = kt * 16 + q4 * 4 + jj; if ((c * 64 - 128 + j) < 0) sacc[kt][jj] = -1e30f; }
;         }
;         float m = -3e38f;
; #pragma unroll
;         for (int kt = 0; kt < 12; ++kt)
; #pragma unroll
;             for (int jj = 0; jj < 4; ++jj) m = fmaxf(m, sacc[kt][jj]);
;         m = fmaxf(m, __shfl_xor(m, 16)); m = fmaxf(m, __shfl_xor(m, 32)); m = fmaxf(m, sink);
;         float l = 0.f;
; #pragma unroll
;         for (int kt = 0; kt < 12; ++kt)
; #pragma unroll
;             for (int jj = 0; jj < 4; ++jj) { const float pr = __builtin_amdgcn_exp2f(sacc[kt][jj] - m); sacc[kt][jj] = pr; l += pr; }
;         l += __shfl_xor(l, 16); l += __shfl_xor(l, 32); l += __builtin_amdgcn_exp2f(sink - m);
;         const float inv = 1.f / l;
;         f32x4 oacc[4];
; #pragma unroll
;         for (int dt = 0; dt < 4; ++dt) oacc[dt] = (f32x4){0.f, 0.f, 0.f, 0.f};
; #pragma unroll
;         for (int kb = 0; kb < 6; ++kb) {
;             const bf16x8 pf = pack8(sacc[2 * kb], sacc[2 * kb + 1]);
;             bf16x4 l0, h0, l1, h1, l2, h2, l3, h3;
;             const unsigned vk = va + (unsigned)(kb * 32 * 144);
;             asm volatile("ds_read_b64_tr_b16 %0, %8\n\tds_read_b64_tr_b16 %1, %8 offset:2304\n\t"
;                          "ds_read_b64_tr_b16 %2, %8 offset:32\n\tds_read_b64_tr_b16 %3, %8 offset:2336\n\t"
;                          "ds_read_b64_tr_b16 %4, %8 offset:64\n\tds_read_b64_tr_b16 %5, %8 offset:2368\n\t"
;                          "ds_read_b64_tr_b16 %6, %8 offset:96\n\tds_read_b64_tr_b16 %7, %8 offset:2400\n\t"
;                          "s_waitcnt lgkmcnt(0)"
;                          : "=&v"(l0), "=&v"(h0), "=&v"(l1), "=&v"(h1), "=&v"(l2), "=&v"(h2), "=&v"(l3), "=&v"(h3) : "v"(vk) : "memory");
;             oacc[0] = MFMA16(cat4(l0, h0), pf, oacc[0]); oacc[1] = MFMA16(cat4(l1, h1), pf, oacc[1]);
.LBB0_332:
	v_add_f32_e32 v44, 0xc3000000, v96
	v_fma_f32 v44, v70, |v44|, v16
	v_add_f32_e32 v16, 0xc3010000, v96
	v_fma_f32 v45, v70, |v16|, v17
	v_add_f32_e32 v16, 0xc3020000, v96
	v_fma_f32 v46, v70, |v16|, v18
	v_add_f32_e32 v16, 0xc3030000, v96
	v_fma_f32 v47, v70, |v16|, v19
	v_add_f32_e32 v16, 0xc3100000, v96
	v_fma_f32 v54, v70, |v16|, v20
	v_add_f32_e32 v16, 0xc3110000, v96
	v_fma_f32 v97, v70, |v16|, v21
	v_add_f32_e32 v16, 0xc3120000, v96
	v_fma_f32 v123, v70, |v16|, v22
	v_add_f32_e32 v16, 0xc3130000, v96
	v_fma_f32 v124, v70, |v16|, v23
	v_add_f32_e32 v16, 0xc3200000, v96
	v_fma_f32 v125, v70, |v16|, v28
	v_add_f32_e32 v16, 0xc3210000, v96
	v_fma_f32 v126, v70, |v16|, v29
	v_add_f32_e32 v16, 0xc3220000, v96
	v_fma_f32 v127, v70, |v16|, v30
	v_add_f32_e32 v16, 0xc3230000, v96
	v_fma_f32 v21, v70, |v16|, v31
	v_add_f32_e32 v16, 0xc3300000, v96
	v_fma_f32 v20, v70, |v16|, v24
	v_add_f32_e32 v16, 0xc3310000, v96
	v_fma_f32 v19, v70, |v16|, v25
	v_add_f32_e32 v16, 0xc3320000, v96
	v_fma_f32 v18, v70, |v16|, v26
	v_add_f32_e32 v16, 0xc3330000, v96
	s_mov_b32 s52, 0xff61b1e6
	v_fma_f32 v17, v70, |v16|, v27
	v_max3_f32 v16, v100, s52, v101
	v_max3_f32 v16, v16, v98, v99
	v_max3_f32 v16, v16, v40, v41
	v_max3_f32 v16, v16, v42, v43
	v_max3_f32 v16, v16, v36, v37
	v_max3_f32 v16, v16, v38, v39
	v_max3_f32 v16, v16, v34, v35
	v_max3_f32 v16, v16, v32, v33
	v_max3_f32 v16, v16, v84, v85
	v_max3_f32 v16, v16, v48, v49
	v_max3_f32 v16, v16, v88, v89
	v_max3_f32 v16, v16, v50, v51
	v_max3_f32 v16, v16, v92, v93
	v_max3_f32 v16, v16, v86, v87
	v_max3_f32 v16, v16, v94, v95
	v_max3_f32 v16, v16, v90, v91
	v_max3_f32 v16, v16, v44, v45
	v_max3_f32 v16, v16, v46, v47
	v_max3_f32 v16, v16, v54, v97
	v_max3_f32 v16, v16, v123, v124
	v_max3_f32 v16, v16, v125, v126
	v_max3_f32 v16, v16, v127, v21
	v_max3_f32 v16, v16, v20, v19
	v_max3_f32 v16, v16, v18, v17
	v_mov_b32_e32 v22, v16
	s_xor_b64 s[50:51], s[50:51], -1
	s_mov_b32 s52, 16
	s_waitcnt lgkmcnt(0)
	v_permlane16_swap_b32_e32 v22, v16
	s_nop 1
	v_max_f32_e32 v16, v16, v22
	v_mov_b32_e32 v22, v16
	s_nop 1
	v_permlane32_swap_b32_e32 v22, v16
	s_nop 1
	v_max3_f32 v16, v16, v22, v120
	v_sub_f32_e32 v22, v100, v16
	v_exp_f32_e32 v22, v22
	v_sub_f32_e32 v24, v101, v16
	v_exp_f32_e32 v24, v24
	v_sub_f32_e32 v25, v98, v16
	v_exp_f32_e32 v25, v25
	v_sub_f32_e32 v26, v99, v16
	v_exp_f32_e32 v26, v26
	v_sub_f32_e32 v27, v40, v16
	v_add_f32_e32 v23, 0, v22
	v_exp_f32_e32 v27, v27
	v_sub_f32_e32 v28, v41, v16
	v_add_f32_e32 v23, v24, v23
	v_exp_f32_e32 v28, v28
	v_sub_f32_e32 v29, v42, v16
	v_add_f32_e32 v23, v25, v23
	v_exp_f32_e32 v29, v29
	v_sub_f32_e32 v30, v43, v16
	v_add_f32_e32 v23, v26, v23
	v_exp_f32_e32 v30, v30
	v_sub_f32_e32 v31, v36, v16
	v_add_f32_e32 v23, v27, v23
	v_exp_f32_e32 v42, v31
	v_sub_f32_e32 v31, v37, v16
	v_add_f32_e32 v23, v28, v23
	v_exp_f32_e32 v43, v31
	v_sub_f32_e32 v31, v38, v16
	v_add_f32_e32 v23, v29, v23
	v_exp_f32_e32 v96, v31
	v_sub_f32_e32 v31, v39, v16
	v_add_f32_e32 v23, v30, v23
	v_exp_f32_e32 v98, v31
	v_sub_f32_e32 v31, v34, v16
	v_add_f32_e32 v23, v42, v23
	v_exp_f32_e32 v99, v31
	v_sub_f32_e32 v31, v35, v16
	v_add_f32_e32 v23, v43, v23
	v_exp_f32_e32 v100, v31
	v_sub_f32_e32 v31, v32, v16
	v_add_f32_e32 v23, v96, v23
	v_exp_f32_e32 v101, v31
	v_sub_f32_e32 v31, v33, v16
	v_add_f32_e32 v23, v98, v23
	v_exp_f32_e32 v128, v31
	v_sub_f32_e32 v31, v84, v16
	v_add_f32_e32 v23, v99, v23
	v_exp_f32_e32 v129, v31
	v_sub_f32_e32 v31, v85, v16
	v_add_f32_e32 v23, v100, v23
	v_exp_f32_e32 v130, v31
	v_sub_f32_e32 v31, v48, v16
	v_add_f32_e32 v23, v101, v23
	v_exp_f32_e32 v131, v31
	v_sub_f32_e32 v31, v49, v16
	v_add_f32_e32 v23, v128, v23
	v_exp_f32_e32 v132, v31
	v_sub_f32_e32 v31, v88, v16
	v_add_f32_e32 v23, v129, v23
	v_exp_f32_e32 v133, v31
	v_sub_f32_e32 v31, v89, v16
	v_add_f32_e32 v23, v130, v23
	v_exp_f32_e32 v134, v31
	v_sub_f32_e32 v31, v50, v16
	v_add_f32_e32 v23, v131, v23
	v_exp_f32_e32 v50, v31
	v_sub_f32_e32 v31, v51, v16
	v_add_f32_e32 v23, v132, v23
	v_exp_f32_e32 v51, v31
	v_sub_f32_e32 v31, v92, v16
	v_add_f32_e32 v23, v133, v23
	v_exp_f32_e32 v92, v31
	v_sub_f32_e32 v31, v93, v16
	v_add_f32_e32 v23, v134, v23
	v_exp_f32_e32 v93, v31
	v_sub_f32_e32 v31, v86, v16
	v_add_f32_e32 v23, v50, v23
	v_exp_f32_e32 v135, v31
	v_sub_f32_e32 v31, v87, v16
	v_add_f32_e32 v23, v51, v23
	v_exp_f32_e32 v138, v31
	v_sub_f32_e32 v31, v94, v16
	v_add_f32_e32 v23, v92, v23
	v_exp_f32_e32 v94, v31
	v_sub_f32_e32 v31, v95, v16
	v_add_f32_e32 v23, v93, v23
	v_exp_f32_e32 v95, v31
	v_sub_f32_e32 v31, v90, v16
	v_add_f32_e32 v23, v135, v23
	v_exp_f32_e32 v139, v31
	v_sub_f32_e32 v31, v91, v16
	v_add_f32_e32 v23, v138, v23
	v_exp_f32_e32 v140, v31
	v_sub_f32_e32 v31, v44, v16
	v_add_f32_e32 v23, v94, v23
	v_exp_f32_e32 v141, v31
	v_add_f32_e32 v23, v95, v23
	v_sub_f32_e32 v45, v45, v16
	v_add_f32_e32 v23, v139, v23
	v_exp_f32_e32 v142, v45
	v_sub_f32_e32 v45, v46, v16
	v_add_f32_e32 v23, v140, v23
	v_exp_f32_e32 v143, v45
	v_sub_f32_e32 v45, v47, v16
	v_add_f32_e32 v44, v141, v23
	v_cvt_pk_bf16_f32 v22, v22, v24
	v_cvt_pk_bf16_f32 v23, v25, v26
	v_cvt_pk_bf16_f32 v24, v27, v28
	v_cvt_pk_bf16_f32 v25, v29, v30
	ds_read_b64_tr_b16 v[38:39], v108
	ds_read_b64_tr_b16 v[40:41], v108 offset:2304
	ds_read_b64_tr_b16 v[34:35], v108 offset:32
	ds_read_b64_tr_b16 v[36:37], v108 offset:2336
	ds_read_b64_tr_b16 v[30:31], v108 offset:64
	ds_read_b64_tr_b16 v[32:33], v108 offset:2368
	ds_read_b64_tr_b16 v[26:27], v108 offset:96
	ds_read_b64_tr_b16 v[28:29], v108 offset:2400
	s_waitcnt lgkmcnt(0)
; #define MFMA16(a, b, c) __builtin_amdgcn_mfma_f32_16x16x32_bf16((a), (b), (c), 0, 0, 0)
; __device__ __forceinline__ void attn_item(const Params& p, LAS unsigned char* L, int item, bf16_t* Yd, int ldd) {
;     ...
;         l += __shfl_xor(l, 16); l += __shfl_xor(l, 32); l += __builtin_amdgcn_exp2f(sink - m);
;         const float inv = 1.f / l;
;         f32x4 oacc[4];
; #pragma unroll
;         for (int dt = 0; dt < 4; ++dt) oacc[dt] = (f32x4){0.f, 0.f, 0.f, 0.f};
; #pragma unroll
;         for (int kb = 0; kb < 6; ++kb) {
;             const bf16x8 pf = pack8(sacc[2 * kb], sacc[2 * kb + 1]);
;             bf16x4 l0, h0, l1, h1, l2, h2, l3, h3;
;             const unsigned vk = va + (unsigned)(kb * 32 * 144);
;             asm volatile("ds_read_b64_tr_b16 %0, %8\n\tds_read_b64_tr_b16 %1, %8 offset:2304\n\t"
;                          "ds_read_b64_tr_b16 %2, %8 offset:32\n\tds_read_b64_tr_b16 %3, %8 offset:2336\n\t"
;                          "ds_read_b64_tr_b16 %4, %8 offset:64\n\tds_read_b64_tr_b16 %5, %8 offset:2368\n\t"
;                          "ds_read_b64_tr_b16 %6, %8 offset:96\n\tds_read_b64_tr_b16 %7, %8 offset:2400\n\t"
;                          "s_waitcnt lgkmcnt(0)"
;                          : "=&v"(l0), "=&v"(h0), "=&v"(l1), "=&v"(h1), "=&v"(l2), "=&v"(h2), "=&v"(l3), "=&v"(h3) : "v"(vk) : "memory");
;             oacc[0] = MFMA16(cat4(l0, h0), pf, oacc[0]); oacc[1] = MFMA16(cat4(l1, h1), pf, oacc[1]);
;             oacc[2] = MFMA16(cat4(l2, h2), pf, oacc[2]); oacc[3] = MFMA16(cat4(l3, h3), pf, oacc[3]);
;         }
; #pragma unroll
;         for (int dt = 0; dt < 4; ++dt) {
;             const u32x2 gq = gv[dt];
;             const f32x4 o = oacc[dt] * inv;
	v_exp_f32_e32 v144, v45
	v_mfma_f32_16x16x32_bf16 v[38:41], v[38:41], v[22:25], 0
	v_add_f32_e32 v44, v142, v44
	v_add_f32_e32 v44, v143, v44
	v_add_f32_e32 v145, v144, v44
	v_mfma_f32_16x16x32_bf16 v[34:37], v[34:37], v[22:25], 0
	v_sub_f32_e32 v54, v54, v16
	v_exp_f32_e32 v54, v54
	v_sub_f32_e32 v21, v21, v16
	v_mfma_f32_16x16x32_bf16 v[30:33], v[30:33], v[22:25], 0
	v_sub_f32_e32 v20, v20, v16
	v_sub_f32_e32 v19, v19, v16
	v_sub_f32_e32 v18, v18, v16
	v_mfma_f32_16x16x32_bf16 v[22:25], v[26:29], v[22:25], 0
	v_cvt_pk_bf16_f32 v26, v42, v43
	v_cvt_pk_bf16_f32 v27, v96, v98
	v_cvt_pk_bf16_f32 v28, v99, v100
	v_cvt_pk_bf16_f32 v29, v101, v128
	ds_read_b64_tr_b16 v[88:89], v111
	ds_read_b64_tr_b16 v[90:91], v111 offset:2304
	ds_read_b64_tr_b16 v[84:85], v111 offset:32
	ds_read_b64_tr_b16 v[86:87], v111 offset:2336
	ds_read_b64_tr_b16 v[46:47], v111 offset:64
	ds_read_b64_tr_b16 v[48:49], v111 offset:2368
	ds_read_b64_tr_b16 v[42:43], v111 offset:96
	ds_read_b64_tr_b16 v[44:45], v111 offset:2400
	s_waitcnt lgkmcnt(0)
	v_sub_f32_e32 v99, v124, v16
	v_mfma_f32_16x16x32_bf16 v[38:41], v[88:91], v[26:29], v[38:41]
	v_sub_f32_e32 v88, v97, v16
	v_exp_f32_e32 v96, v88
	v_sub_f32_e32 v100, v127, v16
	v_mfma_f32_16x16x32_bf16 v[34:37], v[84:87], v[26:29], v[34:37]
	v_sub_f32_e32 v84, v123, v16
	v_exp_f32_e32 v97, v84
	v_add_f32_e32 v84, v54, v145
	v_mfma_f32_16x16x32_bf16 v[30:33], v[46:49], v[26:29], v[30:33]
	v_add_f32_e32 v46, v96, v84
	v_add_f32_e32 v98, v97, v46
	v_sub_f32_e32 v17, v17, v16
	v_mfma_f32_16x16x32_bf16 v[22:25], v[42:45], v[26:29], v[22:25]
	v_cvt_pk_bf16_f32 v26, v129, v130
	v_cvt_pk_bf16_f32 v27, v131, v132
	v_cvt_pk_bf16_f32 v28, v133, v134
	v_cvt_pk_bf16_f32 v29, v50, v51
	ds_read_b64_tr_b16 v[88:89], v112
	ds_read_b64_tr_b16 v[90:91], v112 offset:2304
	ds_read_b64_tr_b16 v[84:85], v112 offset:32
	ds_read_b64_tr_b16 v[86:87], v112 offset:2336
	ds_read_b64_tr_b16 v[46:47], v112 offset:64
	ds_read_b64_tr_b16 v[48:49], v112 offset:2368
	ds_read_b64_tr_b16 v[42:43], v112 offset:96
	ds_read_b64_tr_b16 v[44:45], v112 offset:2400
	s_waitcnt lgkmcnt(0)
	v_exp_f32_e32 v50, v99
	v_sub_f32_e32 v51, v125, v16
	v_exp_f32_e32 v51, v51
	v_mfma_f32_16x16x32_bf16 v[34:37], v[84:87], v[26:29], v[34:37]
	v_sub_f32_e32 v84, v126, v16
	v_exp_f32_e32 v99, v84
	v_add_f32_e32 v84, v50, v98
	v_mfma_f32_16x16x32_bf16 v[38:41], v[88:91], v[26:29], v[38:41]
	v_exp_f32_e32 v17, v17
	v_sub_f32_e32 v16, v120, v16
	v_exp_f32_e32 v16, v16
	v_mfma_f32_16x16x32_bf16 v[30:33], v[46:49], v[26:29], v[30:33]
	v_add_f32_e32 v46, v51, v84
	v_add_f32_e32 v98, v99, v46
	v_mfma_f32_16x16x32_bf16 v[22:25], v[42:45], v[26:29], v[22:25]
	v_cvt_pk_bf16_f32 v26, v92, v93
	v_exp_f32_e32 v92, v100
	v_exp_f32_e32 v93, v21
	v_cvt_pk_bf16_f32 v27, v135, v138
	v_cvt_pk_bf16_f32 v28, v94, v95
	v_exp_f32_e32 v94, v20
	v_add_f32_e32 v20, v92, v98
	v_add_f32_e32 v20, v93, v20
	v_cvt_pk_bf16_f32 v29, v139, v140
	ds_read_b64_tr_b16 v[88:89], v113
	ds_read_b64_tr_b16 v[90:91], v113 offset:2304
	ds_read_b64_tr_b16 v[84:85], v113 offset:32
	ds_read_b64_tr_b16 v[86:87], v113 offset:2336
	ds_read_b64_tr_b16 v[46:47], v113 offset:64
	ds_read_b64_tr_b16 v[48:49], v113 offset:2368
	ds_read_b64_tr_b16 v[42:43], v113 offset:96
	ds_read_b64_tr_b16 v[44:45], v113 offset:2400
	s_waitcnt lgkmcnt(0)
	v_add_f32_e32 v95, v94, v20
	v_mfma_f32_16x16x32_bf16 v[38:41], v[88:91], v[26:29], v[38:41]
	v_mfma_f32_16x16x32_bf16 v[34:37], v[84:87], v[26:29], v[34:37]
	v_mfma_f32_16x16x32_bf16 v[30:33], v[46:49], v[26:29], v[30:33]
	v_mfma_f32_16x16x32_bf16 v[20:23], v[42:45], v[26:29], v[22:25]
	v_cvt_pk_bf16_f32 v24, v141, v142
	v_cvt_pk_bf16_f32 v25, v143, v144
	v_cvt_pk_bf16_f32 v26, v54, v96
	v_cvt_pk_bf16_f32 v27, v97, v50
	v_exp_f32_e32 v50, v19
	v_exp_f32_e32 v54, v18
	ds_read_b64_tr_b16 v[88:89], v114
	ds_read_b64_tr_b16 v[90:91], v114 offset:2304
	ds_read_b64_tr_b16 v[84:85], v114 offset:32
	ds_read_b64_tr_b16 v[86:87], v114 offset:2336
	ds_read_b64_tr_b16 v[46:47], v114 offset:64
	ds_read_b64_tr_b16 v[48:49], v114 offset:2368
	ds_read_b64_tr_b16 v[42:43], v114 offset:96
	ds_read_b64_tr_b16 v[44:45], v114 offset:2400
	s_waitcnt lgkmcnt(0)
	v_add_f32_e32 v18, v50, v95
	v_add_f32_e32 v18, v54, v18
	v_mfma_f32_16x16x32_bf16 v[28:31], v[46:49], v[24:27], v[30:33]
	s_nop 2
	v_add_f32_e32 v32, v17, v18
	ds_bpermute_b32 v33, v121, v32
	v_mfma_f32_16x16x32_bf16 v[38:41], v[88:91], v[24:27], v[38:41]
	v_mfma_f32_16x16x32_bf16 v[34:37], v[84:87], v[24:27], v[34:37]
	v_mfma_f32_16x16x32_bf16 v[18:21], v[42:45], v[24:27], v[20:23]
	v_cvt_pk_bf16_f32 v22, v51, v99
	v_cvt_pk_bf16_f32 v23, v92, v93
	v_cvt_pk_bf16_f32 v24, v94, v50
	v_cvt_pk_bf16_f32 v25, v54, v17
	s_waitcnt lgkmcnt(0)
	v_add_f32_e32 v17, v32, v33
	ds_bpermute_b32 v26, v122, v17
	ds_read_b64_tr_b16 v[88:89], v115
	ds_read_b64_tr_b16 v[90:91], v115 offset:2304
	ds_read_b64_tr_b16 v[84:85], v115 offset:32
	ds_read_b64_tr_b16 v[86:87], v115 offset:2336
	ds_read_b64_tr_b16 v[46:47], v115 offset:64
	ds_read_b64_tr_b16 v[48:49], v115 offset:2368
	ds_read_b64_tr_b16 v[42:43], v115 offset:96
	ds_read_b64_tr_b16 v[44:45], v115 offset:2400
	s_waitcnt lgkmcnt(0)
	s_waitcnt lgkmcnt(0)
	v_add_f32_e32 v17, v17, v26
	v_mfma_f32_16x16x32_bf16 v[32:35], v[84:87], v[22:25], v[34:37]
	s_nop 2
	v_add_f32_e32 v36, v16, v17
	v_mfma_f32_16x16x32_bf16 v[26:29], v[46:49], v[22:25], v[28:31]
	s_nop 2
	v_div_scale_f32 v30, vcc, v36, v36, 1.0
	v_rcp_f32_e32 v31, v30
	v_mfma_f32_16x16x32_bf16 v[16:19], v[42:45], v[22:25], v[18:21]
	s_nop 2
	v_fma_f32 v20, -v30, v31, 1.0
	v_fmac_f32_e32 v31, v20, v31
	v_div_scale_f32 v20, vcc, 1.0, v36, 1.0
	v_mul_f32_e32 v21, v20, v31
	v_mfma_f32_16x16x32_bf16 v[38:41], v[88:91], v[22:25], v[38:41]
	v_fma_f32 v22, -v30, v21, v20
	v_fmac_f32_e32 v21, v22, v31
	v_fma_f32 v20, -v30, v21, v20
	v_div_fmas_f32 v20, v20, v31, v21
	v_div_fixup_f32 v20, v20, v36, 1.0
	s_nop 2
	v_pk_mul_f32 v[22:23], v[40:41], v[20:21] op_sel_hi:[1,0]
	s_waitcnt vmcnt(3)
; __device__ __forceinline__ unsigned cvt_pk_bf16(float lo, float hi) { unsigned r; asm volatile("v_cvt_pk_bf16_f32 %0, %1, %2" : "=v"(r) : "v"(lo), "v"(hi)); return r; }
; __device__ __forceinline__ float bflo(unsigned w) { return __uint_as_float(w << 16); }
; __device__ __forceinline__ float bfhi(unsigned w) { return __uint_as_float(w & 0xffff0000u); }
; __device__ __forceinline__ float siluf(float x) { return x * rcpf_(1.f + __expf(-x)); }
; __device__ __forceinline__ void attn_item(const Params& p, LAS unsigned char* L, int item, bf16_t* Yd, int ldd) {
;     ...
;         for (int dt = 0; dt < 4; ++dt) {
;             const u32x2 gq = gv[dt];
;             const f32x4 o = oacc[dt] * inv;
;             u32x2 wv; wv.x = cvt_pk_bf16(o[0] * siluf(bflo(gq.x)), o[1] * siluf(bfhi(gq.x))); wv.y = cvt_pk_bf16(o[2] * siluf(bflo(gq.y)), o[3] * siluf(bfhi(gq.y)));
;             *(u32x2*)(Yd + (row0 + i) * ldd + h * 64 + dt * 16 + q4 * 4) = wv;
;         }
	v_lshlrev_b32_e32 v21, 16, v82
	v_mul_f32_e32 v24, 0xbfb8aa3b, v21
	v_and_b32_e32 v31, 0xffff0000, v82
	v_exp_f32_e32 v30, v24
	v_mul_f32_e32 v24, 0xbfb8aa3b, v31
	v_exp_f32_e32 v36, v24
	v_pk_mul_f32 v[24:25], v[38:39], v[20:21] op_sel_hi:[1,0]
	v_add_f32_e32 v30, 1.0, v30
	v_rcp_f32_e32 v30, v30
	v_add_f32_e32 v36, 1.0, v36
	v_rcp_f32_e32 v36, v36
	s_andn2_b64 vcc, exec, s[50:51]
	v_mul_f32_e32 v21, v30, v21
	v_lshlrev_b32_e32 v30, 16, v83
	v_mul_f32_e32 v21, v21, v24
	v_mul_f32_e32 v24, v36, v31
	v_mul_f32_e32 v31, 0xbfb8aa3b, v30
	v_and_b32_e32 v36, 0xffff0000, v83
	v_exp_f32_e32 v31, v31
	v_mul_f32_e32 v37, 0xbfb8aa3b, v36
	v_exp_f32_e32 v37, v37
	v_mul_f32_e32 v24, v24, v25
	v_add_f32_e32 v25, 1.0, v31
	v_rcp_f32_e32 v25, v25
	v_add_f32_e32 v31, 1.0, v37
	v_rcp_f32_e32 v31, v31
	v_cvt_pk_bf16_f32 v24, v21, v24
	v_mul_f32_e32 v21, v25, v30
	v_mul_f32_e32 v21, v21, v22
	v_mul_f32_e32 v22, v31, v36
	v_mul_f32_e32 v22, v22, v23
	v_cvt_pk_bf16_f32 v25, v21, v22
	s_waitcnt vmcnt(2)
	v_lshlrev_b32_e32 v21, 16, v80
	v_mul_f32_e32 v22, 0xbfb8aa3b, v21
	v_and_b32_e32 v30, 0xffff0000, v80
	global_store_dwordx2 v[74:75], v[24:25], off
	v_exp_f32_e32 v24, v22
	v_mul_f32_e32 v22, 0xbfb8aa3b, v30
	v_exp_f32_e32 v25, v22
	v_pk_mul_f32 v[22:23], v[34:35], v[20:21] op_sel_hi:[1,0]
	v_add_f32_e32 v24, 1.0, v24
	v_rcp_f32_e32 v31, v24
	v_add_f32_e32 v24, 1.0, v25
	v_rcp_f32_e32 v34, v24
	v_pk_mul_f32 v[24:25], v[32:33], v[20:21] op_sel_hi:[1,0]
	v_mul_f32_e32 v21, v31, v21
	v_mul_f32_e32 v21, v21, v24
	v_mul_f32_e32 v24, v34, v30
	v_lshlrev_b32_e32 v30, 16, v81
	v_mul_f32_e32 v31, 0xbfb8aa3b, v30
	v_and_b32_e32 v32, 0xffff0000, v81
	v_exp_f32_e32 v31, v31
	v_mul_f32_e32 v33, 0xbfb8aa3b, v32
	v_exp_f32_e32 v33, v33
	v_mul_f32_e32 v24, v24, v25
	v_add_f32_e32 v25, 1.0, v31
	v_rcp_f32_e32 v25, v25
	v_add_f32_e32 v31, 1.0, v33
	v_rcp_f32_e32 v31, v31
	v_cvt_pk_bf16_f32 v24, v21, v24
	v_mul_f32_e32 v21, v25, v30
	v_mul_f32_e32 v21, v21, v22
	v_mul_f32_e32 v22, v31, v32
	v_mul_f32_e32 v22, v22, v23
	v_cvt_pk_bf16_f32 v25, v21, v22
	s_waitcnt vmcnt(2)
	v_lshlrev_b32_e32 v21, 16, v78
	v_mul_f32_e32 v22, 0xbfb8aa3b, v21
	v_and_b32_e32 v30, 0xffff0000, v78
	global_store_dwordx2 v[74:75], v[24:25], off offset:32
	v_exp_f32_e32 v24, v22
	v_mul_f32_e32 v22, 0xbfb8aa3b, v30
	v_exp_f32_e32 v25, v22
	v_pk_mul_f32 v[22:23], v[28:29], v[20:21] op_sel_hi:[1,0]
	v_add_f32_e32 v24, 1.0, v24
	v_rcp_f32_e32 v28, v24
	v_add_f32_e32 v24, 1.0, v25
	v_rcp_f32_e32 v29, v24
	v_pk_mul_f32 v[24:25], v[26:27], v[20:21] op_sel_hi:[1,0]
	v_lshlrev_b32_e32 v26, 16, v79
	v_mul_f32_e32 v21, v28, v21
	v_mul_f32_e32 v27, 0xbfb8aa3b, v26
	v_and_b32_e32 v28, 0xffff0000, v79
	v_mul_f32_e32 v21, v21, v24
	v_mul_f32_e32 v24, v29, v30
	v_exp_f32_e32 v27, v27
	v_mul_f32_e32 v29, 0xbfb8aa3b, v28
	v_exp_f32_e32 v29, v29
	v_mul_f32_e32 v24, v24, v25
	v_add_f32_e32 v25, 1.0, v27
	v_rcp_f32_e32 v25, v25
	v_add_f32_e32 v27, 1.0, v29
	v_rcp_f32_e32 v27, v27
	v_cvt_pk_bf16_f32 v24, v21, v24
	v_mul_f32_e32 v21, v25, v26
	v_mul_f32_e32 v21, v21, v22
	v_mul_f32_e32 v22, v27, v28
	v_mul_f32_e32 v22, v22, v23
	v_cvt_pk_bf16_f32 v25, v21, v22
	s_waitcnt vmcnt(2)
	v_lshlrev_b32_e32 v21, 16, v76
	v_mul_f32_e32 v22, 0xbfb8aa3b, v21
	v_and_b32_e32 v23, 0xffff0000, v76
	global_store_dwordx2 v[74:75], v[24:25], off offset:64
	v_exp_f32_e32 v22, v22
	v_mul_f32_e32 v24, 0xbfb8aa3b, v23
	v_exp_f32_e32 v24, v24
	v_pk_mul_f32 v[18:19], v[18:19], v[20:21] op_sel_hi:[1,0]
	v_add_f32_e32 v22, 1.0, v22
	v_rcp_f32_e32 v22, v22
	v_add_f32_e32 v24, 1.0, v24
	v_rcp_f32_e32 v24, v24
	v_pk_mul_f32 v[16:17], v[16:17], v[20:21] op_sel_hi:[1,0]
	v_mul_f32_e32 v20, v22, v21
	v_lshlrev_b32_e32 v21, 16, v77
	v_mul_f32_e32 v16, v20, v16
	v_mul_f32_e32 v20, v24, v23
	v_mul_f32_e32 v22, 0xbfb8aa3b, v21
	v_and_b32_e32 v23, 0xffff0000, v77
	v_exp_f32_e32 v22, v22
	v_mul_f32_e32 v24, 0xbfb8aa3b, v23
	v_exp_f32_e32 v24, v24
	v_mul_f32_e32 v17, v20, v17
	v_add_f32_e32 v20, 1.0, v22
	v_rcp_f32_e32 v20, v20
	v_add_f32_e32 v22, 1.0, v24
	v_rcp_f32_e32 v22, v22
	v_cvt_pk_bf16_f32 v16, v16, v17
	v_mul_f32_e32 v17, v20, v21
	v_mul_f32_e32 v17, v17, v18
	v_mul_f32_e32 v18, v22, v23
	s_mov_b64 s[50:51], 0
	v_mul_f32_e32 v18, v18, v19
	v_cvt_pk_bf16_f32 v17, v17, v18
	global_store_dwordx2 v[74:75], v[16:17], off offset:96
	s_cbranch_vccz .LBB0_309
; #define LAS __attribute__((address_space(3)))
; #define MFMA16(a, b, c) __builtin_amdgcn_mfma_f32_16x16x32_bf16((a), (b), (c), 0, 0, 0)
; __device__ __forceinline__ void attn_item(const Params& p, LAS unsigned char* L, int item, bf16_t* Yd, int ldd) {
;     ...
;         const int i = i0 + qt * 16 + r16;
;         const bf16x8 qa = qt ? qf[1][0] : qf[0][0], qb = qt ? qf[1][1] : qf[0][1];
;         u32x2 gv[4];
; #pragma unroll
;         for (int dt = 0; dt < 4; ++dt) gv[dt] = *(const u32x2*)(Yb + (row0 + i) * 2048 + h * 64 + dt * 16 + q4 * 4);
;         f32x4 sacc[12];
; #pragma unroll
;         for (int kt = 0; kt < 12; ++kt) {
;             const bf16x8 kf0 = *(const LAS bf16x8*)(Ks + (kt * 16 + r16) * 72 + q4 * 8), kf1 = *(const LAS bf16x8*)(Ks + (kt * 16 + r16) * 72 + 32 + q4 * 8);
;             f32x4 a = {0.f, 0.f, 0.f, 0.f}; a = MFMA16(kf0, qa, a); a = MFMA16(kf1, qb, a); sacc[kt] = a;
;         }
;         const float dbase = (float)(128 + i - q4 * 4);
; #pragma unroll
;         for (int kt = 0; kt < 12; ++kt)
; #pragma unroll
;             for (int jj = 0; jj < 4; ++jj) sacc[kt][jj] = fmaf(-slope, fabsf(dbase - (float)(kt * 16 + jj)), sacc[kt][jj]);
;         if (!smp && c < 2) {
; #pragma unroll
;             for (int kt = 0; kt < 8; ++kt)
; #pragma unroll
;                 for (int jj = 0; jj < 4; ++jj) { const int j = kt * 16 + q4 * 4 + jj; if ((c * 64 - 128 + j) < 0) sacc[kt][jj] = -1e30f; }
.LBB0_333:
	v_or_b32_e32 v54, s52, v52
	v_lshl_add_u64 v[16:17], s[54:55], 0, v[54:55]
	v_lshlrev_b64 v[16:17], 12, v[16:17]
	v_lshl_add_u64 v[74:75], v[68:69], 0, v[16:17]
	global_load_dwordx2 v[82:83], v[74:75], off
	global_load_dwordx2 v[80:81], v[74:75], off offset:32
	global_load_dwordx2 v[78:79], v[74:75], off offset:64
	global_load_dwordx2 v[76:77], v[74:75], off offset:96
	ds_read_b128 v[146:149], v110
	ds_read_b128 v[150:153], v110 offset:64
	ds_read_b128 v[154:157], v110 offset:2304
	ds_read_b128 v[158:161], v110 offset:2368
	ds_read_b128 v[162:165], v110 offset:4608
	ds_read_b128 v[166:169], v110 offset:4672
	v_cndmask_b32_e64 v27, v11, v3, s[50:51]
	v_cndmask_b32_e64 v26, v10, v2, s[50:51]
	v_cndmask_b32_e64 v25, v9, v1, s[50:51]
	v_cndmask_b32_e64 v24, v8, v0, s[50:51]
	ds_read_b128 v[170:173], v110 offset:6912
	ds_read_b128 v[174:177], v110 offset:6976
	ds_read_b128 v[178:181], v110 offset:9216
	ds_read_b128 v[182:185], v110 offset:9280
	v_cndmask_b32_e64 v51, v15, v7, s[50:51]
	v_cndmask_b32_e64 v50, v14, v6, s[50:51]
	v_cndmask_b32_e64 v49, v13, v5, s[50:51]
	v_cndmask_b32_e64 v48, v12, v4, s[50:51]
	ds_read_b128 v[186:189], v110 offset:11520
	ds_read_b128 v[190:193], v110 offset:11584
	ds_read_b128 v[194:197], v110 offset:13824
	ds_read_b128 v[198:201], v110 offset:13888
	s_andn2_b64 vcc, exec, s[0:1]
	s_waitcnt lgkmcnt(10)
	v_mfma_f32_16x16x32_bf16 v[32:35], v[146:149], v[24:27], 0
	v_mfma_f32_16x16x32_bf16 v[40:43], v[154:157], v[24:27], 0
	v_mfma_f32_16x16x32_bf16 v[32:35], v[150:153], v[48:51], v[32:35]
	v_mfma_f32_16x16x32_bf16 v[40:43], v[158:161], v[48:51], v[40:43]
	ds_read_b128 v[202:205], v110 offset:16128
	ds_read_b128 v[206:209], v110 offset:16192
	ds_read_b128 v[210:213], v110 offset:18432
	ds_read_b128 v[214:217], v110 offset:18496
	s_waitcnt lgkmcnt(10)
	v_mfma_f32_16x16x32_bf16 v[36:39], v[162:165], v[24:27], 0
	v_mfma_f32_16x16x32_bf16 v[44:47], v[170:173], v[24:27], 0
	v_mfma_f32_16x16x32_bf16 v[36:39], v[166:169], v[48:51], v[36:39]
	v_mfma_f32_16x16x32_bf16 v[44:47], v[174:177], v[48:51], v[44:47]
	ds_read_b128 v[218:221], v110 offset:20736
	ds_read_b128 v[222:225], v110 offset:20800
	ds_read_b128 v[226:229], v110 offset:23040
	ds_read_b128 v[230:233], v110 offset:23104
	s_waitcnt lgkmcnt(10)
	v_mfma_f32_16x16x32_bf16 v[84:87], v[178:181], v[24:27], 0
	v_mfma_f32_16x16x32_bf16 v[88:91], v[186:189], v[24:27], 0
	v_mfma_f32_16x16x32_bf16 v[84:87], v[182:185], v[48:51], v[84:87]
	v_mfma_f32_16x16x32_bf16 v[88:91], v[190:193], v[48:51], v[88:91]
	ds_read_b128 v[234:237], v110 offset:25344
	ds_read_b128 v[238:241], v110 offset:25408
	s_waitcnt lgkmcnt(8)
	v_mfma_f32_16x16x32_bf16 v[92:95], v[194:197], v[24:27], 0
	v_mfma_f32_16x16x32_bf16 v[98:101], v[202:205], v[24:27], 0
	v_mfma_f32_16x16x32_bf16 v[92:95], v[198:201], v[48:51], v[92:95]
	v_mfma_f32_16x16x32_bf16 v[98:101], v[206:209], v[48:51], v[98:101]
	s_waitcnt lgkmcnt(4)
	v_mfma_f32_16x16x32_bf16 v[16:19], v[210:213], v[24:27], 0
	v_mfma_f32_16x16x32_bf16 v[20:23], v[218:221], v[24:27], 0
	v_mfma_f32_16x16x32_bf16 v[16:19], v[214:217], v[48:51], v[16:19]
	v_mfma_f32_16x16x32_bf16 v[20:23], v[222:225], v[48:51], v[20:23]
	s_waitcnt lgkmcnt(0)
	v_mfma_f32_16x16x32_bf16 v[28:31], v[226:229], v[24:27], 0
	v_mfma_f32_16x16x32_bf16 v[24:27], v[234:237], v[24:27], 0
	v_mfma_f32_16x16x32_bf16 v[28:31], v[230:233], v[48:51], v[28:31]
	v_mfma_f32_16x16x32_bf16 v[24:27], v[238:241], v[48:51], v[24:27]
	v_sub_u32_e32 v48, v54, v107
	v_add_u32_e32 v48, 0x80, v48
	v_cvt_f32_u32_e32 v96, v48
	v_pk_add_f32 v[48:49], v[96:97], s[80:81] op_sel_hi:[0,1]
	v_pk_add_f32 v[50:51], v[96:97], s[86:87] op_sel_hi:[0,1]
	v_and_b32_e32 v51, 0x7fffffff, v51
	v_and_b32_e32 v50, 0x7fffffff, v50
	v_and_b32_e32 v49, 0x7fffffff, v49
	v_and_b32_e32 v48, 0x7fffffff, v48
	v_pk_fma_f32 v[48:49], v[72:73], v[48:49], v[86:87]
	v_pk_fma_f32 v[84:85], v[70:71], v[50:51], v[84:85]
	v_pk_add_f32 v[50:51], v[96:97], s[88:89] op_sel_hi:[0,1]
	v_pk_add_f32 v[86:87], v[96:97], s[90:91] op_sel_hi:[0,1]
	v_and_b32_e32 v87, 0x7fffffff, v87
	v_and_b32_e32 v86, 0x7fffffff, v86
	v_and_b32_e32 v51, 0x7fffffff, v51
	v_and_b32_e32 v50, 0x7fffffff, v50
	v_pk_fma_f32 v[50:51], v[72:73], v[50:51], v[90:91]
	v_pk_fma_f32 v[88:89], v[70:71], v[86:87], v[88:89]
	v_pk_add_f32 v[86:87], v[96:97], s[92:93] op_sel_hi:[0,1]
	v_pk_add_f32 v[90:91], v[96:97], s[94:95] op_sel_hi:[0,1]
	v_and_b32_e32 v91, 0x7fffffff, v91
	v_and_b32_e32 v90, 0x7fffffff, v90
	v_and_b32_e32 v87, 0x7fffffff, v87
	v_and_b32_e32 v86, 0x7fffffff, v86
	v_pk_fma_f32 v[86:87], v[72:73], v[86:87], v[94:95]
	v_pk_fma_f32 v[92:93], v[70:71], v[90:91], v[92:93]
	v_pk_add_f32 v[90:91], v[96:97], s[96:97] op_sel_hi:[0,1]
	v_pk_add_f32 v[94:95], v[96:97], s[48:49] op_sel_hi:[0,1]
	v_and_b32_e32 v95, 0x7fffffff, v95
	v_and_b32_e32 v94, 0x7fffffff, v94
	v_and_b32_e32 v91, 0x7fffffff, v91
	v_and_b32_e32 v90, 0x7fffffff, v90
	v_pk_fma_f32 v[90:91], v[72:73], v[90:91], v[100:101]
	v_pk_fma_f32 v[94:95], v[70:71], v[94:95], v[98:99]
	s_cbranch_vccz .LBB0_331
	v_add_f32_e32 v54, -1.0, v96
	v_and_b32_e32 v97, 0x7fffffff, v54
	v_pk_add_f32 v[98:99], v[96:97], s[56:57] op_sel_hi:[0,1]
	v_and_b32_e32 v99, 0x7fffffff, v99
	v_and_b32_e32 v98, 0x7fffffff, v98
	v_pk_fma_f32 v[98:99], v[72:73], v[98:99], v[34:35]
	v_pk_fma_f32 v[100:101], v[70:71], v[96:97], v[32:33]
	v_pk_add_f32 v[32:33], v[96:97], s[58:59] op_sel_hi:[0,1]
	v_pk_add_f32 v[34:35], v[96:97], s[64:65] op_sel_hi:[0,1]
	v_and_b32_e32 v35, 0x7fffffff, v35
	v_and_b32_e32 v34, 0x7fffffff, v34
	v_and_b32_e32 v33, 0x7fffffff, v33
	v_and_b32_e32 v32, 0x7fffffff, v32
	v_pk_fma_f32 v[42:43], v[72:73], v[32:33], v[42:43]
	v_pk_fma_f32 v[40:41], v[70:71], v[34:35], v[40:41]
	v_pk_add_f32 v[32:33], v[96:97], s[68:69] op_sel_hi:[0,1]
	v_pk_add_f32 v[34:35], v[96:97], s[74:75] op_sel_hi:[0,1]
	v_and_b32_e32 v35, 0x7fffffff, v35
	v_and_b32_e32 v34, 0x7fffffff, v34
	v_and_b32_e32 v33, 0x7fffffff, v33
	v_and_b32_e32 v32, 0x7fffffff, v32
	v_pk_fma_f32 v[38:39], v[72:73], v[32:33], v[38:39]
	v_pk_fma_f32 v[36:37], v[70:71], v[34:35], v[36:37]
	v_pk_add_f32 v[32:33], v[96:97], s[76:77] op_sel_hi:[0,1]
	v_pk_add_f32 v[34:35], v[96:97], s[78:79] op_sel_hi:[0,1]
	v_and_b32_e32 v35, 0x7fffffff, v35
	v_and_b32_e32 v34, 0x7fffffff, v34
	v_and_b32_e32 v33, 0x7fffffff, v33
	v_and_b32_e32 v32, 0x7fffffff, v32
	v_pk_fma_f32 v[32:33], v[72:73], v[32:33], v[46:47]
	v_pk_fma_f32 v[34:35], v[70:71], v[34:35], v[44:45]
	s_branch .LBB0_332
